# k-loop re-pipelined, LDS-DMA issues and next-tile fragment reads both packed in the first 8 MFMA slots of the second k-half
# baseline (speedup 1.0000x reference)
; template <int EPI>
; __device__ __forceinline__ void gemm_tile(const bf16_t* __restrict__ A, const int lda, const bf16_t* __restrict__ Bt, const int ldb,
;                                           const int K, const int m0, const int n0, void* Cout, const int ldc, char* lds, const int tid) {
;     ...
;   for (int kt = 0; kt < nt; ++kt) {
;     asm volatile("s_waitcnt vmcnt(0)" ::: "memory");
;     __syncthreads();
;     if (kt + 1 < nt) stageB(kt + 1, (kt + 1) & 1);
;     const char* sa = lds + (kt & 1) * 32768;
;     const char* sb = sa + 16384;
;     bf16x8 af[2][4], bfr[2][4];
; #pragma unroll
;     for (int ks = 0; ks < 2; ++ks) {
; #pragma unroll
;       for (int m = 0; m < 4; ++m) af[ks][m] = *(const bf16x8*)(sa + (wr * 64 + m * 16 + fr) * 128 + (ks ? xk1 : xk0));
; #pragma unroll
;       for (int n = 0; n < 4; ++n) bfr[ks][n] = *(const bf16x8*)(sb + (wc * 64 + n * 16 + fr) * 128 + (ks ? xk1 : xk0));
;     }
;     if (kt + 1 < nt) stageA(kt + 1, (kt + 1) & 1);
; #pragma unroll
;     for (int ks = 0; ks < 2; ++ks)
; #pragma unroll
;       for (int m = 0; m < 4; ++m)
; #pragma unroll
;         for (int n = 0; n < 4; ++n) acc[m][n] = __builtin_amdgcn_mfma_f32_16x16x32_bf16(bfr[ks][n], af[ks][m], acc[m][n], 0, 0, 0);
;   }
.LBB0_104:
	s_add_i32 s25, s26, 0x8000
	s_and_b32 s23, s25, 0x8000
	s_and_b32 s26, s26, 0x8000
	s_waitcnt lgkmcnt(0)
	v_mfma_f32_16x16x32_bf16 v[64:67], v[190:193], v[104:107], v[64:67]
	v_or_b32_e32 v216, s26, v175
	v_add_u32_e32 v222, v216, v181
	v_mfma_f32_16x16x32_bf16 v[60:63], v[194:197], v[104:107], v[60:63]
	v_add_u32_e32 v224, v216, v180
	ds_read_b128 v[206:209], v222
	v_mfma_f32_16x16x32_bf16 v[56:59], v[198:201], v[104:107], v[56:59]
	ds_read_b128 v[210:213], v222 offset:2048
	ds_read_b128 v[92:95], v222 offset:4096
	v_mfma_f32_16x16x32_bf16 v[52:55], v[202:205], v[104:107], v[52:55]
	ds_read_b128 v[68:71], v222 offset:6144
	ds_read_b128 v[88:91], v224 offset:16384
	v_mfma_f32_16x16x32_bf16 v[36:39], v[190:193], v[100:103], v[36:39]
	ds_read_b128 v[80:83], v224 offset:18432
	ds_read_b128 v[72:75], v224 offset:20480
	v_mfma_f32_16x16x32_bf16 v[28:31], v[194:197], v[100:103], v[28:31]
	ds_read_b128 v[76:79], v224 offset:22528
	v_or_b32_e32 v214, s23, v174
	v_mfma_f32_16x16x32_bf16 v[20:23], v[198:201], v[100:103], v[20:23]
	v_add_u32_e32 v218, v214, v181
	v_add_u32_e32 v220, v214, v180
	v_mfma_f32_16x16x32_bf16 v[24:27], v[202:205], v[100:103], v[24:27]
	v_readfirstlane_b32 s100, v176
	s_add_i32 s100, s100, s26
	v_mfma_f32_16x16x32_bf16 v[8:11], v[190:193], v[96:99], v[8:11]
	s_add_u32 s62, s34, 0x80
	s_addc_u32 s63, s35, 0
	v_mfma_f32_16x16x32_bf16 v[16:19], v[194:197], v[96:99], v[16:19]
	v_mfma_f32_16x16x32_bf16 v[32:35], v[198:201], v[96:99], v[32:35]
	v_mfma_f32_16x16x32_bf16 v[48:51], v[202:205], v[96:99], v[48:51]
	v_mfma_f32_16x16x32_bf16 v[44:47], v[190:193], v[84:87], v[44:47]
	v_mfma_f32_16x16x32_bf16 v[40:43], v[194:197], v[84:87], v[40:43]
	v_mfma_f32_16x16x32_bf16 v[12:15], v[198:201], v[84:87], v[12:15]
	v_mfma_f32_16x16x32_bf16 v[4:7], v[202:205], v[84:87], v[4:7]
	s_waitcnt vmcnt(0) lgkmcnt(0)
	s_barrier
	s_cmpk_eq_i32 s34, 0x1500
	s_cbranch_scc1 .Lr_last_104
	v_mfma_f32_16x16x32_bf16 v[64:67], v[88:91], v[206:209], v[64:67]
	s_add_i32 m0, s100, 0x4000
	v_lshl_add_u64 v[226:227], v[140:141], 0, s[62:63]
	global_load_lds_dwordx4 v[226:227], off
	ds_read_b128 v[104:107], v218
	v_mfma_f32_16x16x32_bf16 v[60:63], v[80:83], v[206:209], v[60:63]
	s_add_i32 m0, s100, 0x5000
	v_lshl_add_u64 v[226:227], v[142:143], 0, s[62:63]
	global_load_lds_dwordx4 v[226:227], off
	ds_read_b128 v[100:103], v218 offset:2048
	v_mfma_f32_16x16x32_bf16 v[56:59], v[72:75], v[206:209], v[56:59]
	s_add_i32 m0, s100, 0x6000
	v_lshl_add_u64 v[226:227], v[144:145], 0, s[62:63]
	global_load_lds_dwordx4 v[226:227], off
	ds_read_b128 v[96:99], v218 offset:4096
	v_mfma_f32_16x16x32_bf16 v[52:55], v[76:79], v[206:209], v[52:55]
	s_add_i32 m0, s100, 0x7000
	v_lshl_add_u64 v[226:227], v[146:147], 0, s[62:63]
	global_load_lds_dwordx4 v[226:227], off
	ds_read_b128 v[84:87], v218 offset:6144
	v_mfma_f32_16x16x32_bf16 v[36:39], v[88:91], v[210:213], v[36:39]
	s_mov_b32 m0, s100
	v_lshl_add_u64 v[226:227], v[148:149], 0, s[62:63]
	global_load_lds_dwordx4 v[226:227], off
	ds_read_b128 v[190:193], v220 offset:16384
	v_mfma_f32_16x16x32_bf16 v[28:31], v[80:83], v[210:213], v[28:31]
	s_add_i32 m0, s100, 0x1000
	v_lshl_add_u64 v[226:227], v[150:151], 0, s[62:63]
	global_load_lds_dwordx4 v[226:227], off
	ds_read_b128 v[194:197], v220 offset:18432
	v_mfma_f32_16x16x32_bf16 v[20:23], v[72:75], v[210:213], v[20:23]
	s_add_i32 m0, s100, 0x2000
	v_lshl_add_u64 v[226:227], v[152:153], 0, s[62:63]
	global_load_lds_dwordx4 v[226:227], off
	ds_read_b128 v[198:201], v220 offset:20480
	v_mfma_f32_16x16x32_bf16 v[24:27], v[76:79], v[210:213], v[24:27]
	s_add_i32 m0, s100, 0x3000
	v_lshl_add_u64 v[226:227], v[154:155], 0, s[62:63]
	global_load_lds_dwordx4 v[226:227], off
	ds_read_b128 v[202:205], v220 offset:22528
	v_mfma_f32_16x16x32_bf16 v[8:11], v[88:91], v[92:95], v[8:11]
	v_mfma_f32_16x16x32_bf16 v[16:19], v[80:83], v[92:95], v[16:19]
	v_mfma_f32_16x16x32_bf16 v[32:35], v[72:75], v[92:95], v[32:35]
	v_mfma_f32_16x16x32_bf16 v[48:51], v[76:79], v[92:95], v[48:51]
	v_mfma_f32_16x16x32_bf16 v[44:47], v[88:91], v[68:71], v[44:47]
	v_mfma_f32_16x16x32_bf16 v[40:43], v[80:83], v[68:71], v[40:43]
	v_mfma_f32_16x16x32_bf16 v[12:15], v[72:75], v[68:71], v[12:15]
	v_mfma_f32_16x16x32_bf16 v[4:7], v[76:79], v[68:71], v[4:7]
	s_add_u32 s34, s34, 0x80
	s_addc_u32 s35, s35, 0
	s_mov_b32 s26, s25
	s_branch .LBB0_104

; template <int EPI>
; __device__ __forceinline__ void gemm_tile(const bf16_t* __restrict__ A, const int lda, const bf16_t* __restrict__ Bt, const int ldb,
;                                           const int K, const int m0, const int n0, void* Cout, const int ldc, char* lds, const int tid) {
;     ...
;   for (int kt = 0; kt < nt; ++kt) {
;     asm volatile("s_waitcnt vmcnt(0)" ::: "memory");
;     __syncthreads();
;     if (kt + 1 < nt) stageB(kt + 1, (kt + 1) & 1);
;     const char* sa = lds + (kt & 1) * 32768;
;     const char* sb = sa + 16384;
;     bf16x8 af[2][4], bfr[2][4];
; #pragma unroll
;     for (int ks = 0; ks < 2; ++ks) {
; #pragma unroll
;       for (int m = 0; m < 4; ++m) af[ks][m] = *(const bf16x8*)(sa + (wr * 64 + m * 16 + fr) * 128 + (ks ? xk1 : xk0));
; #pragma unroll
;       for (int n = 0; n < 4; ++n) bfr[ks][n] = *(const bf16x8*)(sb + (wc * 64 + n * 16 + fr) * 128 + (ks ? xk1 : xk0));
;     }
;     if (kt + 1 < nt) stageA(kt + 1, (kt + 1) & 1);
; #pragma unroll
;     for (int ks = 0; ks < 2; ++ks)
; #pragma unroll
;       for (int m = 0; m < 4; ++m)
; #pragma unroll
;         for (int n = 0; n < 4; ++n) acc[m][n] = __builtin_amdgcn_mfma_f32_16x16x32_bf16(bfr[ks][n], af[ks][m], acc[m][n], 0, 0, 0);
;   }
.LBB0_111:
	s_add_i32 s26, s27, 0x8000
	s_and_b32 s29, s26, 0x8000
	s_and_b32 s27, s27, 0x8000
	s_waitcnt lgkmcnt(0)
	v_mfma_f32_16x16x32_bf16 v[64:67], v[184:187], v[104:107], v[64:67]
	v_or_b32_e32 v216, s27, v176
	v_add_u32_e32 v222, v216, v182
	v_mfma_f32_16x16x32_bf16 v[60:63], v[188:191], v[104:107], v[60:63]
	v_add_u32_e32 v224, v216, v181
	ds_read_b128 v[200:203], v222
	v_mfma_f32_16x16x32_bf16 v[56:59], v[192:195], v[104:107], v[56:59]
	ds_read_b128 v[204:207], v222 offset:2048
	ds_read_b128 v[92:95], v222 offset:4096
	v_mfma_f32_16x16x32_bf16 v[52:55], v[196:199], v[104:107], v[52:55]
	ds_read_b128 v[68:71], v222 offset:6144
	ds_read_b128 v[88:91], v224 offset:16384
	v_mfma_f32_16x16x32_bf16 v[48:51], v[184:187], v[100:103], v[48:51]
	ds_read_b128 v[80:83], v224 offset:18432
	ds_read_b128 v[72:75], v224 offset:20480
	v_mfma_f32_16x16x32_bf16 v[44:47], v[188:191], v[100:103], v[44:47]
	ds_read_b128 v[76:79], v224 offset:22528
	v_or_b32_e32 v214, s29, v175
	v_mfma_f32_16x16x32_bf16 v[36:39], v[192:195], v[100:103], v[36:39]
	v_add_u32_e32 v218, v214, v182
	v_add_u32_e32 v220, v214, v181
	v_mfma_f32_16x16x32_bf16 v[40:43], v[196:199], v[100:103], v[40:43]
	v_readfirstlane_b32 s100, v177
	s_add_i32 s100, s100, s27
	v_mfma_f32_16x16x32_bf16 v[32:35], v[184:187], v[96:99], v[32:35]
	s_add_u32 s62, s2, 0x80
	s_addc_u32 s63, s3, 0
	v_mfma_f32_16x16x32_bf16 v[24:27], v[188:191], v[96:99], v[24:27]
	v_mfma_f32_16x16x32_bf16 v[28:31], v[192:195], v[96:99], v[28:31]
	v_mfma_f32_16x16x32_bf16 v[20:23], v[196:199], v[96:99], v[20:23]
	v_mfma_f32_16x16x32_bf16 v[16:19], v[184:187], v[84:87], v[16:19]
	v_mfma_f32_16x16x32_bf16 v[12:15], v[188:191], v[84:87], v[12:15]
	v_mfma_f32_16x16x32_bf16 v[8:11], v[192:195], v[84:87], v[8:11]
	v_mfma_f32_16x16x32_bf16 v[4:7], v[196:199], v[84:87], v[4:7]
	s_waitcnt vmcnt(0) lgkmcnt(0)
	s_barrier
	s_cmpk_eq_i32 s2, 0x700
	s_cbranch_scc1 .Lr_last_111
	v_mfma_f32_16x16x32_bf16 v[64:67], v[88:91], v[200:203], v[64:67]
	s_add_i32 m0, s100, 0x4000
	v_lshl_add_u64 v[226:227], v[140:141], 0, s[62:63]
	global_load_lds_dwordx4 v[226:227], off
	ds_read_b128 v[104:107], v218
	v_mfma_f32_16x16x32_bf16 v[60:63], v[80:83], v[200:203], v[60:63]
	s_add_i32 m0, s100, 0x5000
	v_lshl_add_u64 v[226:227], v[142:143], 0, s[62:63]
	global_load_lds_dwordx4 v[226:227], off
	ds_read_b128 v[100:103], v218 offset:2048
	v_mfma_f32_16x16x32_bf16 v[56:59], v[72:75], v[200:203], v[56:59]
	s_add_i32 m0, s100, 0x6000
	v_lshl_add_u64 v[226:227], v[144:145], 0, s[62:63]
	global_load_lds_dwordx4 v[226:227], off
	ds_read_b128 v[96:99], v218 offset:4096
	v_mfma_f32_16x16x32_bf16 v[52:55], v[76:79], v[200:203], v[52:55]
	s_add_i32 m0, s100, 0x7000
	v_lshl_add_u64 v[226:227], v[146:147], 0, s[62:63]
	global_load_lds_dwordx4 v[226:227], off
	ds_read_b128 v[84:87], v218 offset:6144
	v_mfma_f32_16x16x32_bf16 v[48:51], v[88:91], v[204:207], v[48:51]
	s_mov_b32 m0, s100
	v_lshl_add_u64 v[226:227], v[148:149], 0, s[62:63]
	global_load_lds_dwordx4 v[226:227], off
	ds_read_b128 v[184:187], v220 offset:16384
	v_mfma_f32_16x16x32_bf16 v[44:47], v[80:83], v[204:207], v[44:47]
	s_add_i32 m0, s100, 0x1000
	v_lshl_add_u64 v[226:227], v[150:151], 0, s[62:63]
	global_load_lds_dwordx4 v[226:227], off
	ds_read_b128 v[188:191], v220 offset:18432
	v_mfma_f32_16x16x32_bf16 v[36:39], v[72:75], v[204:207], v[36:39]
	s_add_i32 m0, s100, 0x2000
	v_lshl_add_u64 v[226:227], v[152:153], 0, s[62:63]
	global_load_lds_dwordx4 v[226:227], off
	ds_read_b128 v[192:195], v220 offset:20480
	v_mfma_f32_16x16x32_bf16 v[40:43], v[76:79], v[204:207], v[40:43]
	s_add_i32 m0, s100, 0x3000
	v_lshl_add_u64 v[226:227], v[154:155], 0, s[62:63]
	global_load_lds_dwordx4 v[226:227], off
	ds_read_b128 v[196:199], v220 offset:22528
	v_mfma_f32_16x16x32_bf16 v[32:35], v[88:91], v[92:95], v[32:35]
	v_mfma_f32_16x16x32_bf16 v[24:27], v[80:83], v[92:95], v[24:27]
	v_mfma_f32_16x16x32_bf16 v[28:31], v[72:75], v[92:95], v[28:31]
	v_mfma_f32_16x16x32_bf16 v[20:23], v[76:79], v[92:95], v[20:23]
	v_mfma_f32_16x16x32_bf16 v[16:19], v[88:91], v[68:71], v[16:19]
	v_mfma_f32_16x16x32_bf16 v[12:15], v[80:83], v[68:71], v[12:15]
	v_mfma_f32_16x16x32_bf16 v[8:11], v[72:75], v[68:71], v[8:11]
	v_mfma_f32_16x16x32_bf16 v[4:7], v[76:79], v[68:71], v[4:7]
	s_add_u32 s2, s2, 0x80
	s_addc_u32 s3, s3, 0
	s_mov_b32 s27, s26
	s_branch .LBB0_111

; template <int EPI>
; __device__ __forceinline__ void gemm_tile(const bf16_t* __restrict__ A, const int lda, const bf16_t* __restrict__ Bt, const int ldb,
;                                           const int K, const int m0, const int n0, void* Cout, const int ldc, char* lds, const int tid) {
;     ...
;   for (int kt = 0; kt < nt; ++kt) {
;     asm volatile("s_waitcnt vmcnt(0)" ::: "memory");
;     __syncthreads();
;     if (kt + 1 < nt) stageB(kt + 1, (kt + 1) & 1);
;     const char* sa = lds + (kt & 1) * 32768;
;     const char* sb = sa + 16384;
;     bf16x8 af[2][4], bfr[2][4];
; #pragma unroll
;     for (int ks = 0; ks < 2; ++ks) {
; #pragma unroll
;       for (int m = 0; m < 4; ++m) af[ks][m] = *(const bf16x8*)(sa + (wr * 64 + m * 16 + fr) * 128 + (ks ? xk1 : xk0));
; #pragma unroll
;       for (int n = 0; n < 4; ++n) bfr[ks][n] = *(const bf16x8*)(sb + (wc * 64 + n * 16 + fr) * 128 + (ks ? xk1 : xk0));
;     }
;     if (kt + 1 < nt) stageA(kt + 1, (kt + 1) & 1);
; #pragma unroll
;     for (int ks = 0; ks < 2; ++ks)
; #pragma unroll
;       for (int m = 0; m < 4; ++m)
; #pragma unroll
;         for (int n = 0; n < 4; ++n) acc[m][n] = __builtin_amdgcn_mfma_f32_16x16x32_bf16(bfr[ks][n], af[ks][m], acc[m][n], 0, 0, 0);
;   }
.LBB0_125:
	s_add_i32 s25, s26, 0x8000
	s_and_b32 s23, s25, 0x8000
	s_and_b32 s26, s26, 0x8000
	s_waitcnt lgkmcnt(0)
	v_mfma_f32_16x16x32_bf16 v[64:67], v[184:187], v[104:107], v[64:67]
	v_or_b32_e32 v216, s26, v175
	v_add_u32_e32 v222, v216, v181
	v_mfma_f32_16x16x32_bf16 v[60:63], v[188:191], v[104:107], v[60:63]
	v_add_u32_e32 v224, v216, v180
	ds_read_b128 v[200:203], v222
	v_mfma_f32_16x16x32_bf16 v[56:59], v[192:195], v[104:107], v[56:59]
	ds_read_b128 v[204:207], v222 offset:2048
	ds_read_b128 v[92:95], v222 offset:4096
	v_mfma_f32_16x16x32_bf16 v[52:55], v[196:199], v[104:107], v[52:55]
	ds_read_b128 v[68:71], v222 offset:6144
	ds_read_b128 v[88:91], v224 offset:16384
	v_mfma_f32_16x16x32_bf16 v[36:39], v[184:187], v[100:103], v[36:39]
	ds_read_b128 v[80:83], v224 offset:18432
	ds_read_b128 v[72:75], v224 offset:20480
	v_mfma_f32_16x16x32_bf16 v[28:31], v[188:191], v[100:103], v[28:31]
	ds_read_b128 v[76:79], v224 offset:22528
	v_or_b32_e32 v214, s23, v174
	v_mfma_f32_16x16x32_bf16 v[20:23], v[192:195], v[100:103], v[20:23]
	v_add_u32_e32 v218, v214, v181
	v_add_u32_e32 v220, v214, v180
	v_mfma_f32_16x16x32_bf16 v[24:27], v[196:199], v[100:103], v[24:27]
	v_readfirstlane_b32 s100, v176
	s_add_i32 s100, s100, s26
	v_mfma_f32_16x16x32_bf16 v[8:11], v[184:187], v[96:99], v[8:11]
	s_add_u32 s62, s34, 0x80
	s_addc_u32 s63, s35, 0
	v_mfma_f32_16x16x32_bf16 v[16:19], v[188:191], v[96:99], v[16:19]
	v_mfma_f32_16x16x32_bf16 v[32:35], v[192:195], v[96:99], v[32:35]
	v_mfma_f32_16x16x32_bf16 v[48:51], v[196:199], v[96:99], v[48:51]
	v_mfma_f32_16x16x32_bf16 v[44:47], v[184:187], v[84:87], v[44:47]
	v_mfma_f32_16x16x32_bf16 v[40:43], v[188:191], v[84:87], v[40:43]
	v_mfma_f32_16x16x32_bf16 v[12:15], v[192:195], v[84:87], v[12:15]
	v_mfma_f32_16x16x32_bf16 v[4:7], v[196:199], v[84:87], v[4:7]
	s_waitcnt vmcnt(0) lgkmcnt(0)
	s_barrier
	s_cmpk_eq_i32 s34, 0x700
	s_cbranch_scc1 .Lr_last_125
	v_mfma_f32_16x16x32_bf16 v[64:67], v[88:91], v[200:203], v[64:67]
	s_add_i32 m0, s100, 0x4000
	v_lshl_add_u64 v[226:227], v[140:141], 0, s[62:63]
	global_load_lds_dwordx4 v[226:227], off
	ds_read_b128 v[104:107], v218
	v_mfma_f32_16x16x32_bf16 v[60:63], v[80:83], v[200:203], v[60:63]
	s_add_i32 m0, s100, 0x5000
	v_lshl_add_u64 v[226:227], v[142:143], 0, s[62:63]
	global_load_lds_dwordx4 v[226:227], off
	ds_read_b128 v[100:103], v218 offset:2048
	v_mfma_f32_16x16x32_bf16 v[56:59], v[72:75], v[200:203], v[56:59]
	s_add_i32 m0, s100, 0x6000
	v_lshl_add_u64 v[226:227], v[144:145], 0, s[62:63]
	global_load_lds_dwordx4 v[226:227], off
	ds_read_b128 v[96:99], v218 offset:4096
	v_mfma_f32_16x16x32_bf16 v[52:55], v[76:79], v[200:203], v[52:55]
	s_add_i32 m0, s100, 0x7000
	v_lshl_add_u64 v[226:227], v[146:147], 0, s[62:63]
	global_load_lds_dwordx4 v[226:227], off
	ds_read_b128 v[84:87], v218 offset:6144
	v_mfma_f32_16x16x32_bf16 v[36:39], v[88:91], v[204:207], v[36:39]
	s_mov_b32 m0, s100
	v_lshl_add_u64 v[226:227], v[148:149], 0, s[62:63]
	global_load_lds_dwordx4 v[226:227], off
	ds_read_b128 v[184:187], v220 offset:16384
	v_mfma_f32_16x16x32_bf16 v[28:31], v[80:83], v[204:207], v[28:31]
	s_add_i32 m0, s100, 0x1000
	v_lshl_add_u64 v[226:227], v[150:151], 0, s[62:63]
	global_load_lds_dwordx4 v[226:227], off
	ds_read_b128 v[188:191], v220 offset:18432
	v_mfma_f32_16x16x32_bf16 v[20:23], v[72:75], v[204:207], v[20:23]
	s_add_i32 m0, s100, 0x2000
	v_lshl_add_u64 v[226:227], v[152:153], 0, s[62:63]
	global_load_lds_dwordx4 v[226:227], off
	ds_read_b128 v[192:195], v220 offset:20480
	v_mfma_f32_16x16x32_bf16 v[24:27], v[76:79], v[204:207], v[24:27]
	s_add_i32 m0, s100, 0x3000
	v_lshl_add_u64 v[226:227], v[154:155], 0, s[62:63]
	global_load_lds_dwordx4 v[226:227], off
	ds_read_b128 v[196:199], v220 offset:22528
	v_mfma_f32_16x16x32_bf16 v[8:11], v[88:91], v[92:95], v[8:11]
	v_mfma_f32_16x16x32_bf16 v[16:19], v[80:83], v[92:95], v[16:19]
	v_mfma_f32_16x16x32_bf16 v[32:35], v[72:75], v[92:95], v[32:35]
	v_mfma_f32_16x16x32_bf16 v[48:51], v[76:79], v[92:95], v[48:51]
	v_mfma_f32_16x16x32_bf16 v[44:47], v[88:91], v[68:71], v[44:47]
	v_mfma_f32_16x16x32_bf16 v[40:43], v[80:83], v[68:71], v[40:43]
	v_mfma_f32_16x16x32_bf16 v[12:15], v[72:75], v[68:71], v[12:15]
	v_mfma_f32_16x16x32_bf16 v[4:7], v[76:79], v[68:71], v[4:7]
	s_add_u32 s34, s34, 0x80
	s_addc_u32 s35, s35, 0
	s_mov_b32 s26, s25
	s_branch .LBB0_125

; template <int EPI>
; __device__ __forceinline__ void gemm_tile(const bf16_t* __restrict__ A, const int lda, const bf16_t* __restrict__ Bt, const int ldb,
;                                           const int K, const int m0, const int n0, void* Cout, const int ldc, char* lds, const int tid) {
;     ...
;   for (int kt = 0; kt < nt; ++kt) {
;     asm volatile("s_waitcnt vmcnt(0)" ::: "memory");
;     __syncthreads();
;     if (kt + 1 < nt) stageB(kt + 1, (kt + 1) & 1);
;     const char* sa = lds + (kt & 1) * 32768;
;     const char* sb = sa + 16384;
;     bf16x8 af[2][4], bfr[2][4];
; #pragma unroll
;     for (int ks = 0; ks < 2; ++ks) {
; #pragma unroll
;       for (int m = 0; m < 4; ++m) af[ks][m] = *(const bf16x8*)(sa + (wr * 64 + m * 16 + fr) * 128 + (ks ? xk1 : xk0));
; #pragma unroll
;       for (int n = 0; n < 4; ++n) bfr[ks][n] = *(const bf16x8*)(sb + (wc * 64 + n * 16 + fr) * 128 + (ks ? xk1 : xk0));
;     }
;     if (kt + 1 < nt) stageA(kt + 1, (kt + 1) & 1);
; #pragma unroll
;     for (int ks = 0; ks < 2; ++ks)
; #pragma unroll
;       for (int m = 0; m < 4; ++m)
; #pragma unroll
;         for (int n = 0; n < 4; ++n) acc[m][n] = __builtin_amdgcn_mfma_f32_16x16x32_bf16(bfr[ks][n], af[ks][m], acc[m][n], 0, 0, 0);
;   }
.LBB0_649:
	s_add_i32 s24, s25, 0x8000
	s_and_b32 s26, s24, 0x8000
	s_and_b32 s25, s25, 0x8000
	s_waitcnt lgkmcnt(0)
	v_mfma_f32_16x16x32_bf16 v[64:67], v[184:187], v[104:107], v[64:67]
	v_or_b32_e32 v216, s25, v176
	v_add_u32_e32 v222, v216, v182
	v_mfma_f32_16x16x32_bf16 v[60:63], v[188:191], v[104:107], v[60:63]
	v_add_u32_e32 v224, v216, v181
	ds_read_b128 v[200:203], v222
	v_mfma_f32_16x16x32_bf16 v[56:59], v[192:195], v[104:107], v[56:59]
	ds_read_b128 v[204:207], v222 offset:2048
	ds_read_b128 v[92:95], v222 offset:4096
	v_mfma_f32_16x16x32_bf16 v[44:47], v[196:199], v[104:107], v[44:47]
	ds_read_b128 v[68:71], v222 offset:6144
	ds_read_b128 v[88:91], v224 offset:16384
	v_mfma_f32_16x16x32_bf16 v[36:39], v[184:187], v[100:103], v[36:39]
	ds_read_b128 v[80:83], v224 offset:18432
	ds_read_b128 v[72:75], v224 offset:20480
	v_mfma_f32_16x16x32_bf16 v[28:31], v[188:191], v[100:103], v[28:31]
	ds_read_b128 v[76:79], v224 offset:22528
	v_or_b32_e32 v214, s26, v175
	v_mfma_f32_16x16x32_bf16 v[12:15], v[192:195], v[100:103], v[12:15]
	v_add_u32_e32 v218, v214, v182
	v_add_u32_e32 v220, v214, v181
	v_mfma_f32_16x16x32_bf16 v[24:27], v[196:199], v[100:103], v[24:27]
	v_readfirstlane_b32 s100, v177
	s_add_i32 s100, s100, s25
	v_mfma_f32_16x16x32_bf16 v[8:11], v[184:187], v[96:99], v[8:11]
	s_add_u32 s62, s34, 0x80
	s_addc_u32 s63, s35, 0
	v_mfma_f32_16x16x32_bf16 v[20:23], v[188:191], v[96:99], v[20:23]
	v_mfma_f32_16x16x32_bf16 v[32:35], v[192:195], v[96:99], v[32:35]
	v_mfma_f32_16x16x32_bf16 v[52:55], v[196:199], v[96:99], v[52:55]
	v_mfma_f32_16x16x32_bf16 v[48:51], v[184:187], v[84:87], v[48:51]
	v_mfma_f32_16x16x32_bf16 v[40:43], v[188:191], v[84:87], v[40:43]
	v_mfma_f32_16x16x32_bf16 v[16:19], v[192:195], v[84:87], v[16:19]
	v_mfma_f32_16x16x32_bf16 v[4:7], v[196:199], v[84:87], v[4:7]
	s_waitcnt vmcnt(0) lgkmcnt(0)
	s_barrier
	s_cmpk_eq_i32 s34, 0x700
	s_cbranch_scc1 .Lr_last_649
	v_mfma_f32_16x16x32_bf16 v[64:67], v[88:91], v[200:203], v[64:67]
	s_add_i32 m0, s100, 0x4000
	v_lshl_add_u64 v[226:227], v[140:141], 0, s[62:63]
	global_load_lds_dwordx4 v[226:227], off
	ds_read_b128 v[104:107], v218
	v_mfma_f32_16x16x32_bf16 v[60:63], v[80:83], v[200:203], v[60:63]
	s_add_i32 m0, s100, 0x5000
	v_lshl_add_u64 v[226:227], v[142:143], 0, s[62:63]
	global_load_lds_dwordx4 v[226:227], off
	ds_read_b128 v[100:103], v218 offset:2048
	v_mfma_f32_16x16x32_bf16 v[56:59], v[72:75], v[200:203], v[56:59]
	s_add_i32 m0, s100, 0x6000
	v_lshl_add_u64 v[226:227], v[144:145], 0, s[62:63]
	global_load_lds_dwordx4 v[226:227], off
	ds_read_b128 v[96:99], v218 offset:4096
	v_mfma_f32_16x16x32_bf16 v[44:47], v[76:79], v[200:203], v[44:47]
	s_add_i32 m0, s100, 0x7000
	v_lshl_add_u64 v[226:227], v[146:147], 0, s[62:63]
	global_load_lds_dwordx4 v[226:227], off
	ds_read_b128 v[84:87], v218 offset:6144
	v_mfma_f32_16x16x32_bf16 v[36:39], v[88:91], v[204:207], v[36:39]
	s_mov_b32 m0, s100
	v_lshl_add_u64 v[226:227], v[148:149], 0, s[62:63]
	global_load_lds_dwordx4 v[226:227], off
	ds_read_b128 v[184:187], v220 offset:16384
	v_mfma_f32_16x16x32_bf16 v[28:31], v[80:83], v[204:207], v[28:31]
	s_add_i32 m0, s100, 0x1000
	v_lshl_add_u64 v[226:227], v[150:151], 0, s[62:63]
	global_load_lds_dwordx4 v[226:227], off
	ds_read_b128 v[188:191], v220 offset:18432
	v_mfma_f32_16x16x32_bf16 v[12:15], v[72:75], v[204:207], v[12:15]
	s_add_i32 m0, s100, 0x2000
	v_lshl_add_u64 v[226:227], v[152:153], 0, s[62:63]
	global_load_lds_dwordx4 v[226:227], off
	ds_read_b128 v[192:195], v220 offset:20480
	v_mfma_f32_16x16x32_bf16 v[24:27], v[76:79], v[204:207], v[24:27]
	s_add_i32 m0, s100, 0x3000
	v_lshl_add_u64 v[226:227], v[154:155], 0, s[62:63]
	global_load_lds_dwordx4 v[226:227], off
	ds_read_b128 v[196:199], v220 offset:22528
	v_mfma_f32_16x16x32_bf16 v[8:11], v[88:91], v[92:95], v[8:11]
	v_mfma_f32_16x16x32_bf16 v[20:23], v[80:83], v[92:95], v[20:23]
	v_mfma_f32_16x16x32_bf16 v[32:35], v[72:75], v[92:95], v[32:35]
	v_mfma_f32_16x16x32_bf16 v[52:55], v[76:79], v[92:95], v[52:55]
	v_mfma_f32_16x16x32_bf16 v[48:51], v[88:91], v[68:71], v[48:51]
	v_mfma_f32_16x16x32_bf16 v[40:43], v[80:83], v[68:71], v[40:43]
	v_mfma_f32_16x16x32_bf16 v[16:19], v[72:75], v[68:71], v[16:19]
	v_mfma_f32_16x16x32_bf16 v[4:7], v[76:79], v[68:71], v[4:7]
	s_add_u32 s34, s34, 0x80
	s_addc_u32 s35, s35, 0
	s_mov_b32 s25, s24
	s_branch .LBB0_649
